# P5_SS1_prefetch
# baseline (speedup 1.0000x reference)
; #define PG8_STAGE(bufoff, gbase, voff) do { _Pragma("unroll") for (int _i = 0; _i < 2; ++_i) \
;         __builtin_amdgcn_global_load_lds((const unsigned*)((const char*)(gbase) + (voff)[_i]), (PG8_LAS unsigned*)(lds + (bufoff) + ldsw + _i * 8192), 16, 0, 0); } while (0)
; #define PG8_LDA(dst, b, h) do { _Pragma("unroll") for (int m = 0; m < 4; ++m) _Pragma("unroll") for (int k = 0; k < 2; ++k) dst[m][k] = *(const PG8_LAS bf16x8*)(lds + PG8_SA(b, h) + aoff + m * 2048 + k * 1024); } while (0)
; #define PG8_LDB(dst, b, h) do { _Pragma("unroll") for (int n = 0; n < 2; ++n) _Pragma("unroll") for (int k = 0; k < 2; ++k) dst[n][k] = *(const PG8_LAS bf16x8*)(lds + PG8_SB(b, h) + boff + n * 2048 + k * 1024); } while (0)
; #define PG8_SCHED __builtin_amdgcn_sched_barrier(0)
;     __device__ __forceinline__ void operator()(const f32x4 (&acc)[2][2][4][2], const Unit& u, int wr, int wc, int fr, int fq) const {
;         const int row0 = u.pm * BM + wr * 64 + fr, col0 = u.pn * HALF + wc * 32 + 8 * fq;
;         float rsv[2][4];
; #pragma unroll
;         for (int ai = 0; ai < 2; ++ai)
; #pragma unroll
;             for (int m = 0; m < 4; ++m) rsv[ai][m] = ss[row0 + ai * HALF + m * 16];
;         asm volatile("" ::: "memory");
; template <class Epi, class Sched, bool ALIGN_EPI = false, bool SP2 = false>
; __device__ __forceinline__ void gemm_phase(PG8_LAS unsigned char* lds, const Gemm g, const Sched& S, const Epi& E) {
;     ...
;         const bool has_next = S.next(ui + 1, nxt);
;         const char* nA = has_next ? (const char*)g.A + (size_t)nxt.pm * tstep : cA; const char* nB = has_next ? (const char*)g.Bt + (size_t)nxt.pn * tstep : cB;
;         for (int t = 0; t < nt; t += 2) {
;             const bool last = (t == nt - 2);
;             const char* a1 = cA + (size_t)(t + 1) * kstep;
;             const char* a2 = last ? nA : cA + (size_t)(t + 2) * kstep; const char* b2 = last ? nB : cB + (size_t)(t + 2) * kstep;
;             const char* a3 = a2 + kstep; const char* b3 = b2 + kstep;
;             if (last && has_next) S.a_ready(nxt);
;             if constexpr (SP2) {
;             PG8_LDB(B0, 0, 0); PG8_LDB(B1, 0, 1); PG8_SCHED; PG8_LDA(At, 0, 0); PG8_STAGE(PG8_SA(1, 1), a1 + hstep, voffA);
.Lp5_unit:
	s_add_u32 s45, s16, 1
	s_mul_i32 s40, s45, s14
	s_add_u32 s40, s40, s2
	s_cmp_lt_u32 s40, 2816
	s_cselect_b32 s19, 1, 0
	s_min_u32 s40, s40, 2815
	s_and_b32 s41, s40, 7
	s_lshr_b32 s42, s40, 3
	s_mul_i32 s41, s41, 352
	s_add_u32 s41, s41, s42
	s_mul_hi_u32 s42, s41, 0xba2e8c
	s_mul_i32 s43, s42, 352
	s_sub_u32 s43, s41, s43
	s_and_b32 s40, s43, 7
	s_lshl_b32 s42, s42, 3
	s_add_u32 s20, s42, s40
	s_lshr_b32 s21, s43, 3
	s_mul_i32 s40, s20, 0x100000
	s_add_u32 s26, s10, s40
	s_addc_u32 s27, s11, 0
	s_mul_i32 s40, s21, 0x100000
	s_add_u32 s28, s12, s40
	s_addc_u32 s29, s13, 0
	s_cmp_eq_u32 s19, 0
	s_cselect_b32 s26, s22, s26
	s_cselect_b32 s27, s23, s27
	s_cselect_b32 s28, s24, s28
	s_cselect_b32 s29, s25, s29
	s_add_u32 s30, s22, s8
	s_addc_u32 s31, s23, 0
	s_add_u32 s32, s24, s8
	s_addc_u32 s33, s25, 0
	s_add_u32 s30, s30, s4
	s_addc_u32 s31, s31, s5
	s_add_u32 s32, s32, s4
	s_addc_u32 s33, s33, s5
	s_add_u32 s30, s30, s4
	s_addc_u32 s31, s31, s5
	s_add_u32 s32, s32, s4
	s_addc_u32 s33, s33, s5
	s_add_u32 s56, s30, 0x80000
	s_addc_u32 s57, s31, 0
	s_add_u32 s58, s32, 0x80000
	s_addc_u32 s59, s33, 0
	s_movk_i32 s34, 16
	v_mov_b32_e32 v0, 0
	v_mov_b32_e32 v1, 0
	v_mov_b32_e32 v2, 0
	v_mov_b32_e32 v3, 0
	v_mov_b32_e32 v4, 0
	v_mov_b32_e32 v5, 0
	v_mov_b32_e32 v6, 0
	v_mov_b32_e32 v7, 0
	v_mov_b32_e32 v8, 0
	v_mov_b32_e32 v9, 0
	v_mov_b32_e32 v10, 0
	v_mov_b32_e32 v11, 0
	v_mov_b32_e32 v12, 0
	v_mov_b32_e32 v13, 0
	v_mov_b32_e32 v14, 0
	v_mov_b32_e32 v15, 0
	v_mov_b32_e32 v16, 0
	v_mov_b32_e32 v17, 0
	v_mov_b32_e32 v18, 0
	v_mov_b32_e32 v19, 0
	v_mov_b32_e32 v20, 0
	v_mov_b32_e32 v21, 0
	v_mov_b32_e32 v22, 0
	v_mov_b32_e32 v23, 0
	v_mov_b32_e32 v24, 0
	v_mov_b32_e32 v25, 0
	v_mov_b32_e32 v26, 0
	v_mov_b32_e32 v27, 0
	v_mov_b32_e32 v28, 0
	v_mov_b32_e32 v29, 0
	v_mov_b32_e32 v30, 0
	v_mov_b32_e32 v31, 0
	v_mov_b32_e32 v32, 0
	v_mov_b32_e32 v33, 0
	v_mov_b32_e32 v34, 0
	v_mov_b32_e32 v35, 0
	v_mov_b32_e32 v36, 0
	v_mov_b32_e32 v37, 0
	v_mov_b32_e32 v38, 0
	v_mov_b32_e32 v39, 0
	v_mov_b32_e32 v40, 0
	v_mov_b32_e32 v41, 0
	v_mov_b32_e32 v42, 0
	v_mov_b32_e32 v43, 0
	v_mov_b32_e32 v44, 0
	v_mov_b32_e32 v45, 0
	v_mov_b32_e32 v46, 0
	v_mov_b32_e32 v47, 0
	v_mov_b32_e32 v48, 0
	v_mov_b32_e32 v49, 0
	v_mov_b32_e32 v50, 0
	v_mov_b32_e32 v51, 0
	v_mov_b32_e32 v52, 0
	v_mov_b32_e32 v53, 0
	v_mov_b32_e32 v54, 0
	v_mov_b32_e32 v55, 0
	v_mov_b32_e32 v56, 0
	v_mov_b32_e32 v57, 0
	v_mov_b32_e32 v58, 0
	v_mov_b32_e32 v59, 0
	v_mov_b32_e32 v60, 0
	v_mov_b32_e32 v61, 0
	v_mov_b32_e32 v62, 0
	v_mov_b32_e32 v63, 0
	v_mov_b32_e32 v64, 0
	v_mov_b32_e32 v65, 0
	v_mov_b32_e32 v66, 0
	v_mov_b32_e32 v67, 0
	v_mov_b32_e32 v68, 0
	v_mov_b32_e32 v69, 0
	v_mov_b32_e32 v70, 0
	v_mov_b32_e32 v71, 0
	v_mov_b32_e32 v72, 0
	v_mov_b32_e32 v73, 0
	v_mov_b32_e32 v74, 0
	v_mov_b32_e32 v75, 0
	v_mov_b32_e32 v76, 0
	v_mov_b32_e32 v77, 0
	v_mov_b32_e32 v78, 0
	v_mov_b32_e32 v79, 0
	v_mov_b32_e32 v80, 0
	v_mov_b32_e32 v81, 0
	v_mov_b32_e32 v82, 0
	v_mov_b32_e32 v83, 0
	v_mov_b32_e32 v84, 0
	v_mov_b32_e32 v85, 0
	v_mov_b32_e32 v86, 0
	v_mov_b32_e32 v87, 0
	v_mov_b32_e32 v88, 0
	v_mov_b32_e32 v89, 0
	v_mov_b32_e32 v90, 0
	v_mov_b32_e32 v91, 0
	v_mov_b32_e32 v92, 0
	v_mov_b32_e32 v93, 0
	v_mov_b32_e32 v94, 0
	v_mov_b32_e32 v95, 0
	v_mov_b32_e32 v96, 0
	v_mov_b32_e32 v97, 0
	v_mov_b32_e32 v98, 0
	v_mov_b32_e32 v99, 0
	v_mov_b32_e32 v100, 0
	v_mov_b32_e32 v101, 0
	v_mov_b32_e32 v102, 0
	v_mov_b32_e32 v103, 0
	v_mov_b32_e32 v104, 0
	v_mov_b32_e32 v105, 0
	v_mov_b32_e32 v106, 0
	v_mov_b32_e32 v107, 0
	v_mov_b32_e32 v108, 0
	v_mov_b32_e32 v109, 0
	v_mov_b32_e32 v110, 0
	v_mov_b32_e32 v111, 0
	v_mov_b32_e32 v112, 0
	v_mov_b32_e32 v113, 0
	v_mov_b32_e32 v114, 0
	v_mov_b32_e32 v115, 0
	v_mov_b32_e32 v116, 0
	v_mov_b32_e32 v117, 0
	v_mov_b32_e32 v118, 0
	v_mov_b32_e32 v119, 0
	v_mov_b32_e32 v120, 0
	v_mov_b32_e32 v121, 0
	v_mov_b32_e32 v122, 0
	v_mov_b32_e32 v123, 0
	v_mov_b32_e32 v124, 0
	v_mov_b32_e32 v125, 0
	v_mov_b32_e32 v126, 0
	v_mov_b32_e32 v127, 0
	s_lshl_b32 s40, s17, 10
	s_add_u32 s48, s76, s40
	s_addc_u32 s49, s77, 0
	v_and_b32_e32 v254, 15, v185
	s_lshl_b32 s40, s37, 6
	v_add_u32_e32 v254, s40, v254
	v_lshlrev_b32_e32 v254, 2, v254
	v_mov_b32_e32 v255, v254
	v_mov_b32_e32 v186, v254
	v_mov_b32_e32 v187, v254
	global_load_dword v254, v254, s[48:49] offset:0
	global_load_dword v255, v255, s[48:49] offset:64
	global_load_dword v186, v186, s[48:49] offset:128
	global_load_dword v187, v187, s[48:49] offset:192
	ds_read_b128 v[196:199], v247 offset:0
	ds_read_b128 v[200:203], v248 offset:0
	ds_read_b128 v[204:207], v247 offset:2048
	ds_read_b128 v[208:211], v248 offset:2048
	ds_read_b128 v[128:131], v245 offset:0
	ds_read_b128 v[132:135], v246 offset:0
	ds_read_b128 v[136:139], v245 offset:2048
	ds_read_b128 v[140:143], v246 offset:2048
	ds_read_b128 v[144:147], v245 offset:4096
	ds_read_b128 v[148:151], v246 offset:4096
	ds_read_b128 v[152:155], v245 offset:6144
	ds_read_b128 v[156:159], v246 offset:6144
	s_cmp_ge_u32 s36, 4
	s_cbranch_scc1 .Lp5_kloop1

; __device__ __forceinline__ unsigned cvt_pk_bf16(float lo, float hi) { unsigned r; asm volatile("v_cvt_pk_bf16_f32 %0, %1, %2" : "=v"(r) : "v"(lo), "v"(hi)); return r; }
;     __device__ __forceinline__ void operator()(const f32x4 (&acc)[2][2][4][2], const Unit& u, int wr, int wc, int fr, int fq) const {
;         const int row0 = u.pm * BM + wr * 64 + fr, col0 = u.pn * HALF + wc * 32 + 8 * fq;
;         float rsv[2][4];
; #pragma unroll
;         for (int ai = 0; ai < 2; ++ai)
; #pragma unroll
;             for (int m = 0; m < 4; ++m) rsv[ai][m] = ss[row0 + ai * HALF + m * 16];
;         asm volatile("" ::: "memory");
; #pragma unroll
;         for (int ai = 0; ai < 2; ++ai)
; #pragma unroll
;             for (int m = 0; m < 4; ++m) { const int row = row0 + ai * HALF + m * 16; const float rs = __builtin_amdgcn_rsqf(rsv[ai][m] * inv_n + eps);
;                 float a[8];
; #pragma unroll
;                 for (int n = 0; n < 2; ++n)
; #pragma unroll
;                     for (int i = 0; i < 4; ++i) { const float g = acc[ai][0][m][n][i] * rs, up = acc[ai][1][m][n][i] * rs;
;                         a[n * 4 + i] = g * __builtin_amdgcn_rcpf(1.0f + __builtin_amdgcn_exp2f(-1.4426950408889634f * g)) * up; }
;                 u32x4 w; w.x = cvt_pk_bf16(a[0], a[1]); w.y = cvt_pk_bf16(a[2], a[3]); w.z = cvt_pk_bf16(a[4], a[5]); w.w = cvt_pk_bf16(a[6], a[7]);
;                 *(u32x4*)(O + (size_t)row * ldc + col0) = w; }
;     }
.Lp5_kdone:
	s_waitcnt lgkmcnt(0)
	s_nop 7
	s_nop 7
	v_mov_b32_e32 v134, v254
	v_mov_b32_e32 v135, v255
	v_mov_b32_e32 v136, v186
	v_mov_b32_e32 v137, v187
	v_and_b32_e32 v254, 63, v185
	v_and_b32_e32 v255, 15, v254
	v_lshrrev_b32_e32 v186, 4, v254
	s_lshl_b32 s40, s37, 6
	v_add_u32_e32 v255, s40, v255
	v_lshlrev_b32_e32 v128, 2, v255
	v_mul_u32_u24_e32 v129, 0x2c00, v255
	s_lshl_b32 s41, s38, 6
	v_lshl_add_u32 v129, v186, 4, v129
	v_add_u32_e32 v129, s41, v129
	v_mov_b32_e32 v130, 0x358637bd
	s_lshl_b32 s40, s17, 10
	s_add_u32 s48, s76, s40
	s_addc_u32 s49, s77, 0
	s_mul_i32 s40, s17, 0x2c0000
	s_lshl_b32 s41, s18, 8
	s_add_u32 s40, s40, s41
	s_add_u32 s50, s76, 0xa800000
	s_addc_u32 s51, s77, 0
	s_add_u32 s50, s50, s40
	s_addc_u32 s51, s51, 0
	global_load_dword v138, v128, s[48:49] offset:512
	global_load_dword v139, v128, s[48:49] offset:576
	global_load_dword v140, v128, s[48:49] offset:640
	global_load_dword v141, v128, s[48:49] offset:704
	v_fmamk_f32 v131, v134, 0x3a000000, v130
	v_add_u32_e32 v132, 0x0, v129
	v_rsq_f32_e32 v131, v131
	s_nop 0
	v_mul_f32_e32 v0, v0, v131
	v_mul_f32_e32 v1, v1, v131
	v_mul_f32_e32 v2, v2, v131
	v_mul_f32_e32 v3, v3, v131
	v_mul_f32_e32 v4, v4, v131
	v_mul_f32_e32 v5, v5, v131
	v_mul_f32_e32 v6, v6, v131
	v_mul_f32_e32 v7, v7, v131
	v_mul_f32_e32 v32, v32, v131
	v_mul_f32_e32 v33, v33, v131
	v_mul_f32_e32 v34, v34, v131
	v_mul_f32_e32 v35, v35, v131
	v_mul_f32_e32 v36, v36, v131
	v_mul_f32_e32 v37, v37, v131
	v_mul_f32_e32 v38, v38, v131
	v_mul_f32_e32 v39, v39, v131
	v_mul_f32_e32 v144, 0xbfb8aa3b, v0
	v_mul_f32_e32 v145, 0xbfb8aa3b, v1
	v_mul_f32_e32 v146, 0xbfb8aa3b, v2
	v_mul_f32_e32 v147, 0xbfb8aa3b, v3
	v_mul_f32_e32 v148, 0xbfb8aa3b, v4
	v_mul_f32_e32 v149, 0xbfb8aa3b, v5
	v_mul_f32_e32 v150, 0xbfb8aa3b, v6
	v_mul_f32_e32 v151, 0xbfb8aa3b, v7
	v_exp_f32_e32 v144, v144
	v_exp_f32_e32 v145, v145
	v_exp_f32_e32 v146, v146
	v_exp_f32_e32 v147, v147
	v_exp_f32_e32 v148, v148
	v_exp_f32_e32 v149, v149
	v_exp_f32_e32 v150, v150
	v_exp_f32_e32 v151, v151
	v_add_f32_e32 v144, 1.0, v144
	v_add_f32_e32 v145, 1.0, v145
	v_add_f32_e32 v146, 1.0, v146
	v_add_f32_e32 v147, 1.0, v147
	v_add_f32_e32 v148, 1.0, v148
	v_add_f32_e32 v149, 1.0, v149
	v_add_f32_e32 v150, 1.0, v150
	v_add_f32_e32 v151, 1.0, v151
	v_rcp_f32_e32 v144, v144
	v_rcp_f32_e32 v145, v145
	v_rcp_f32_e32 v146, v146
	v_rcp_f32_e32 v147, v147
	v_rcp_f32_e32 v148, v148
	v_rcp_f32_e32 v149, v149
	v_rcp_f32_e32 v150, v150
	v_rcp_f32_e32 v151, v151
	v_mul_f32_e32 v0, v0, v144
	v_mul_f32_e32 v1, v1, v145
	v_mul_f32_e32 v2, v2, v146
	v_mul_f32_e32 v3, v3, v147
	v_mul_f32_e32 v4, v4, v148
	v_mul_f32_e32 v5, v5, v149
	v_mul_f32_e32 v6, v6, v150
	v_mul_f32_e32 v7, v7, v151
	v_mul_f32_e32 v0, v32, v0
	v_mul_f32_e32 v1, v33, v1
	v_mul_f32_e32 v2, v34, v2
	v_mul_f32_e32 v3, v35, v3
	v_mul_f32_e32 v4, v36, v4
	v_mul_f32_e32 v5, v37, v5
	v_mul_f32_e32 v6, v38, v6
	v_mul_f32_e32 v7, v39, v7
	v_cvt_pk_bf16_f32 v152, v0, v1
	v_cvt_pk_bf16_f32 v153, v2, v3
	v_cvt_pk_bf16_f32 v154, v4, v5
	v_cvt_pk_bf16_f32 v155, v6, v7
	s_nop 1
	global_store_dwordx4 v132, v[152:155], s[50:51]
	s_nop 1
	v_fmamk_f32 v131, v135, 0x3a000000, v130
	v_add_u32_e32 v132, 0x2c000, v129
	v_rsq_f32_e32 v131, v131
	s_nop 0
	v_mul_f32_e32 v8, v8, v131
	v_mul_f32_e32 v9, v9, v131
	v_mul_f32_e32 v10, v10, v131
	v_mul_f32_e32 v11, v11, v131
	v_mul_f32_e32 v12, v12, v131
	v_mul_f32_e32 v13, v13, v131
	v_mul_f32_e32 v14, v14, v131
	v_mul_f32_e32 v15, v15, v131
	v_mul_f32_e32 v40, v40, v131
	v_mul_f32_e32 v41, v41, v131
	v_mul_f32_e32 v42, v42, v131
	v_mul_f32_e32 v43, v43, v131
	v_mul_f32_e32 v44, v44, v131
	v_mul_f32_e32 v45, v45, v131
	v_mul_f32_e32 v46, v46, v131
	v_mul_f32_e32 v47, v47, v131
	v_mul_f32_e32 v144, 0xbfb8aa3b, v8
	v_mul_f32_e32 v145, 0xbfb8aa3b, v9
	v_mul_f32_e32 v146, 0xbfb8aa3b, v10
	v_mul_f32_e32 v147, 0xbfb8aa3b, v11
	v_mul_f32_e32 v148, 0xbfb8aa3b, v12
	v_mul_f32_e32 v149, 0xbfb8aa3b, v13
	v_mul_f32_e32 v150, 0xbfb8aa3b, v14
	v_mul_f32_e32 v151, 0xbfb8aa3b, v15
	v_exp_f32_e32 v144, v144
	v_exp_f32_e32 v145, v145
	v_exp_f32_e32 v146, v146
	v_exp_f32_e32 v147, v147
	v_exp_f32_e32 v148, v148
	v_exp_f32_e32 v149, v149
	v_exp_f32_e32 v150, v150
	v_exp_f32_e32 v151, v151
	v_add_f32_e32 v144, 1.0, v144
	v_add_f32_e32 v145, 1.0, v145
	v_add_f32_e32 v146, 1.0, v146
	v_add_f32_e32 v147, 1.0, v147
	v_add_f32_e32 v148, 1.0, v148
	v_add_f32_e32 v149, 1.0, v149
	v_add_f32_e32 v150, 1.0, v150
	v_add_f32_e32 v151, 1.0, v151
	v_rcp_f32_e32 v144, v144
	v_rcp_f32_e32 v145, v145
	v_rcp_f32_e32 v146, v146
	v_rcp_f32_e32 v147, v147
	v_rcp_f32_e32 v148, v148
	v_rcp_f32_e32 v149, v149
	v_rcp_f32_e32 v150, v150
	v_rcp_f32_e32 v151, v151
	v_mul_f32_e32 v8, v8, v144
	v_mul_f32_e32 v9, v9, v145
	v_mul_f32_e32 v10, v10, v146
	v_mul_f32_e32 v11, v11, v147
	v_mul_f32_e32 v12, v12, v148
	v_mul_f32_e32 v13, v13, v149
	v_mul_f32_e32 v14, v14, v150
	v_mul_f32_e32 v15, v15, v151
	v_mul_f32_e32 v8, v40, v8
	v_mul_f32_e32 v9, v41, v9
	v_mul_f32_e32 v10, v42, v10
	v_mul_f32_e32 v11, v43, v11
	v_mul_f32_e32 v12, v44, v12
	v_mul_f32_e32 v13, v45, v13
	v_mul_f32_e32 v14, v46, v14
	v_mul_f32_e32 v15, v47, v15
	v_cvt_pk_bf16_f32 v152, v8, v9
	v_cvt_pk_bf16_f32 v153, v10, v11
	v_cvt_pk_bf16_f32 v154, v12, v13
	v_cvt_pk_bf16_f32 v155, v14, v15
	s_nop 1
	global_store_dwordx4 v132, v[152:155], s[50:51]
	s_nop 1
	v_fmamk_f32 v131, v136, 0x3a000000, v130
	v_add_u32_e32 v132, 0x58000, v129
	v_rsq_f32_e32 v131, v131
	s_nop 0
	v_mul_f32_e32 v16, v16, v131
	v_mul_f32_e32 v17, v17, v131
	v_mul_f32_e32 v18, v18, v131
	v_mul_f32_e32 v19, v19, v131
	v_mul_f32_e32 v20, v20, v131
	v_mul_f32_e32 v21, v21, v131
	v_mul_f32_e32 v22, v22, v131
; __device__ __forceinline__ unsigned cvt_pk_bf16(float lo, float hi) { unsigned r; asm volatile("v_cvt_pk_bf16_f32 %0, %1, %2" : "=v"(r) : "v"(lo), "v"(hi)); return r; }
;     __device__ __forceinline__ void operator()(const f32x4 (&acc)[2][2][4][2], const Unit& u, int wr, int wc, int fr, int fq) const {
;     ...
; #pragma unroll
;         for (int ai = 0; ai < 2; ++ai)
; #pragma unroll
;             for (int m = 0; m < 4; ++m) { const int row = row0 + ai * HALF + m * 16; const float rs = __builtin_amdgcn_rsqf(rsv[ai][m] * inv_n + eps);
;                 float a[8];
; #pragma unroll
;                 for (int n = 0; n < 2; ++n)
; #pragma unroll
;                     for (int i = 0; i < 4; ++i) { const float g = acc[ai][0][m][n][i] * rs, up = acc[ai][1][m][n][i] * rs;
;                         a[n * 4 + i] = g * __builtin_amdgcn_rcpf(1.0f + __builtin_amdgcn_exp2f(-1.4426950408889634f * g)) * up; }
;                 u32x4 w; w.x = cvt_pk_bf16(a[0], a[1]); w.y = cvt_pk_bf16(a[2], a[3]); w.z = cvt_pk_bf16(a[4], a[5]); w.w = cvt_pk_bf16(a[6], a[7]);
;                 *(u32x4*)(O + (size_t)row * ldc + col0) = w; }
;     }
	v_mul_f32_e32 v23, v23, v131
	v_mul_f32_e32 v48, v48, v131
	v_mul_f32_e32 v49, v49, v131
	v_mul_f32_e32 v50, v50, v131
	v_mul_f32_e32 v51, v51, v131
	v_mul_f32_e32 v52, v52, v131
	v_mul_f32_e32 v53, v53, v131
	v_mul_f32_e32 v54, v54, v131
	v_mul_f32_e32 v55, v55, v131
	v_mul_f32_e32 v144, 0xbfb8aa3b, v16
	v_mul_f32_e32 v145, 0xbfb8aa3b, v17
	v_mul_f32_e32 v146, 0xbfb8aa3b, v18
	v_mul_f32_e32 v147, 0xbfb8aa3b, v19
	v_mul_f32_e32 v148, 0xbfb8aa3b, v20
	v_mul_f32_e32 v149, 0xbfb8aa3b, v21
	v_mul_f32_e32 v150, 0xbfb8aa3b, v22
	v_mul_f32_e32 v151, 0xbfb8aa3b, v23
	v_exp_f32_e32 v144, v144
	v_exp_f32_e32 v145, v145
	v_exp_f32_e32 v146, v146
	v_exp_f32_e32 v147, v147
	v_exp_f32_e32 v148, v148
	v_exp_f32_e32 v149, v149
	v_exp_f32_e32 v150, v150
	v_exp_f32_e32 v151, v151
	v_add_f32_e32 v144, 1.0, v144
	v_add_f32_e32 v145, 1.0, v145
	v_add_f32_e32 v146, 1.0, v146
	v_add_f32_e32 v147, 1.0, v147
	v_add_f32_e32 v148, 1.0, v148
	v_add_f32_e32 v149, 1.0, v149
	v_add_f32_e32 v150, 1.0, v150
	v_add_f32_e32 v151, 1.0, v151
	v_rcp_f32_e32 v144, v144
	v_rcp_f32_e32 v145, v145
	v_rcp_f32_e32 v146, v146
	v_rcp_f32_e32 v147, v147
	v_rcp_f32_e32 v148, v148
	v_rcp_f32_e32 v149, v149
	v_rcp_f32_e32 v150, v150
	v_rcp_f32_e32 v151, v151
	v_mul_f32_e32 v16, v16, v144
	v_mul_f32_e32 v17, v17, v145
	v_mul_f32_e32 v18, v18, v146
	v_mul_f32_e32 v19, v19, v147
	v_mul_f32_e32 v20, v20, v148
	v_mul_f32_e32 v21, v21, v149
	v_mul_f32_e32 v22, v22, v150
	v_mul_f32_e32 v23, v23, v151
	v_mul_f32_e32 v16, v48, v16
	v_mul_f32_e32 v17, v49, v17
	v_mul_f32_e32 v18, v50, v18
	v_mul_f32_e32 v19, v51, v19
	v_mul_f32_e32 v20, v52, v20
	v_mul_f32_e32 v21, v53, v21
	v_mul_f32_e32 v22, v54, v22
	v_mul_f32_e32 v23, v55, v23
	v_cvt_pk_bf16_f32 v152, v16, v17
	v_cvt_pk_bf16_f32 v153, v18, v19
	v_cvt_pk_bf16_f32 v154, v20, v21
	v_cvt_pk_bf16_f32 v155, v22, v23
	s_nop 1
	global_store_dwordx4 v132, v[152:155], s[50:51]
	s_nop 1
	v_fmamk_f32 v131, v137, 0x3a000000, v130
	v_add_u32_e32 v132, 0x84000, v129
	v_rsq_f32_e32 v131, v131
	s_nop 0
	v_mul_f32_e32 v24, v24, v131
	v_mul_f32_e32 v25, v25, v131
	v_mul_f32_e32 v26, v26, v131
	v_mul_f32_e32 v27, v27, v131
	v_mul_f32_e32 v28, v28, v131
	v_mul_f32_e32 v29, v29, v131
	v_mul_f32_e32 v30, v30, v131
	v_mul_f32_e32 v31, v31, v131
	v_mul_f32_e32 v56, v56, v131
	v_mul_f32_e32 v57, v57, v131
	v_mul_f32_e32 v58, v58, v131
	v_mul_f32_e32 v59, v59, v131
	v_mul_f32_e32 v60, v60, v131
	v_mul_f32_e32 v61, v61, v131
	v_mul_f32_e32 v62, v62, v131
	v_mul_f32_e32 v63, v63, v131
	v_mul_f32_e32 v144, 0xbfb8aa3b, v24
	v_mul_f32_e32 v145, 0xbfb8aa3b, v25
	v_mul_f32_e32 v146, 0xbfb8aa3b, v26
	v_mul_f32_e32 v147, 0xbfb8aa3b, v27
	v_mul_f32_e32 v148, 0xbfb8aa3b, v28
	v_mul_f32_e32 v149, 0xbfb8aa3b, v29
	v_mul_f32_e32 v150, 0xbfb8aa3b, v30
	v_mul_f32_e32 v151, 0xbfb8aa3b, v31
	v_exp_f32_e32 v144, v144
	v_exp_f32_e32 v145, v145
	v_exp_f32_e32 v146, v146
	v_exp_f32_e32 v147, v147
	v_exp_f32_e32 v148, v148
	v_exp_f32_e32 v149, v149
	v_exp_f32_e32 v150, v150
	v_exp_f32_e32 v151, v151
	v_add_f32_e32 v144, 1.0, v144
	v_add_f32_e32 v145, 1.0, v145
	v_add_f32_e32 v146, 1.0, v146
	v_add_f32_e32 v147, 1.0, v147
	v_add_f32_e32 v148, 1.0, v148
	v_add_f32_e32 v149, 1.0, v149
	v_add_f32_e32 v150, 1.0, v150
	v_add_f32_e32 v151, 1.0, v151
	v_rcp_f32_e32 v144, v144
	v_rcp_f32_e32 v145, v145
	v_rcp_f32_e32 v146, v146
	v_rcp_f32_e32 v147, v147
	v_rcp_f32_e32 v148, v148
	v_rcp_f32_e32 v149, v149
	v_rcp_f32_e32 v150, v150
	v_rcp_f32_e32 v151, v151
	v_mul_f32_e32 v24, v24, v144
	v_mul_f32_e32 v25, v25, v145
	v_mul_f32_e32 v26, v26, v146
	v_mul_f32_e32 v27, v27, v147
	v_mul_f32_e32 v28, v28, v148
	v_mul_f32_e32 v29, v29, v149
	v_mul_f32_e32 v30, v30, v150
	v_mul_f32_e32 v31, v31, v151
	v_mul_f32_e32 v24, v56, v24
	v_mul_f32_e32 v25, v57, v25
	v_mul_f32_e32 v26, v58, v26
	v_mul_f32_e32 v27, v59, v27
	v_mul_f32_e32 v28, v60, v28
	v_mul_f32_e32 v29, v61, v29
	v_mul_f32_e32 v30, v62, v30
	v_mul_f32_e32 v31, v63, v31
	v_cvt_pk_bf16_f32 v152, v24, v25
	v_cvt_pk_bf16_f32 v153, v26, v27
	v_cvt_pk_bf16_f32 v154, v28, v29
	v_cvt_pk_bf16_f32 v155, v30, v31
	s_nop 1
	global_store_dwordx4 v132, v[152:155], s[50:51]
	s_nop 1
	s_waitcnt vmcnt(4)
	v_fmamk_f32 v131, v138, 0x3a000000, v130
	v_add_u32_e32 v132, 0x160000, v129
	v_rsq_f32_e32 v131, v131
	s_nop 0
	v_mul_f32_e32 v64, v64, v131
	v_mul_f32_e32 v65, v65, v131
	v_mul_f32_e32 v66, v66, v131
	v_mul_f32_e32 v67, v67, v131
	v_mul_f32_e32 v68, v68, v131
	v_mul_f32_e32 v69, v69, v131
	v_mul_f32_e32 v70, v70, v131
	v_mul_f32_e32 v71, v71, v131
	v_mul_f32_e32 v96, v96, v131
	v_mul_f32_e32 v97, v97, v131
	v_mul_f32_e32 v98, v98, v131
	v_mul_f32_e32 v99, v99, v131
	v_mul_f32_e32 v100, v100, v131
	v_mul_f32_e32 v101, v101, v131
	v_mul_f32_e32 v102, v102, v131
	v_mul_f32_e32 v103, v103, v131
	v_mul_f32_e32 v144, 0xbfb8aa3b, v64
	v_mul_f32_e32 v145, 0xbfb8aa3b, v65
	v_mul_f32_e32 v146, 0xbfb8aa3b, v66
	v_mul_f32_e32 v147, 0xbfb8aa3b, v67
	v_mul_f32_e32 v148, 0xbfb8aa3b, v68
	v_mul_f32_e32 v149, 0xbfb8aa3b, v69
	v_mul_f32_e32 v150, 0xbfb8aa3b, v70
	v_mul_f32_e32 v151, 0xbfb8aa3b, v71
	v_exp_f32_e32 v144, v144
	v_exp_f32_e32 v145, v145
	v_exp_f32_e32 v146, v146
	v_exp_f32_e32 v147, v147
	v_exp_f32_e32 v148, v148
	v_exp_f32_e32 v149, v149
	v_exp_f32_e32 v150, v150
	v_exp_f32_e32 v151, v151
	v_add_f32_e32 v144, 1.0, v144
	v_add_f32_e32 v145, 1.0, v145
	v_add_f32_e32 v146, 1.0, v146
	v_add_f32_e32 v147, 1.0, v147
	v_add_f32_e32 v148, 1.0, v148
	v_add_f32_e32 v149, 1.0, v149
	v_add_f32_e32 v150, 1.0, v150
	v_add_f32_e32 v151, 1.0, v151
	v_rcp_f32_e32 v144, v144
	v_rcp_f32_e32 v145, v145
	v_rcp_f32_e32 v146, v146
	v_rcp_f32_e32 v147, v147
	v_rcp_f32_e32 v148, v148
; __device__ __forceinline__ unsigned cvt_pk_bf16(float lo, float hi) { unsigned r; asm volatile("v_cvt_pk_bf16_f32 %0, %1, %2" : "=v"(r) : "v"(lo), "v"(hi)); return r; }
;     __device__ __forceinline__ void operator()(const f32x4 (&acc)[2][2][4][2], const Unit& u, int wr, int wc, int fr, int fq) const {
;     ...
; #pragma unroll
;         for (int ai = 0; ai < 2; ++ai)
; #pragma unroll
;             for (int m = 0; m < 4; ++m) { const int row = row0 + ai * HALF + m * 16; const float rs = __builtin_amdgcn_rsqf(rsv[ai][m] * inv_n + eps);
;                 float a[8];
; #pragma unroll
;                 for (int n = 0; n < 2; ++n)
; #pragma unroll
;                     for (int i = 0; i < 4; ++i) { const float g = acc[ai][0][m][n][i] * rs, up = acc[ai][1][m][n][i] * rs;
;                         a[n * 4 + i] = g * __builtin_amdgcn_rcpf(1.0f + __builtin_amdgcn_exp2f(-1.4426950408889634f * g)) * up; }
;                 u32x4 w; w.x = cvt_pk_bf16(a[0], a[1]); w.y = cvt_pk_bf16(a[2], a[3]); w.z = cvt_pk_bf16(a[4], a[5]); w.w = cvt_pk_bf16(a[6], a[7]);
;                 *(u32x4*)(O + (size_t)row * ldc + col0) = w; }
;     }
	v_rcp_f32_e32 v149, v149
	v_rcp_f32_e32 v150, v150
	v_rcp_f32_e32 v151, v151
	v_mul_f32_e32 v64, v64, v144
	v_mul_f32_e32 v65, v65, v145
	v_mul_f32_e32 v66, v66, v146
	v_mul_f32_e32 v67, v67, v147
	v_mul_f32_e32 v68, v68, v148
	v_mul_f32_e32 v69, v69, v149
	v_mul_f32_e32 v70, v70, v150
	v_mul_f32_e32 v71, v71, v151
	v_mul_f32_e32 v64, v96, v64
	v_mul_f32_e32 v65, v97, v65
	v_mul_f32_e32 v66, v98, v66
	v_mul_f32_e32 v67, v99, v67
	v_mul_f32_e32 v68, v100, v68
	v_mul_f32_e32 v69, v101, v69
	v_mul_f32_e32 v70, v102, v70
	v_mul_f32_e32 v71, v103, v71
	v_cvt_pk_bf16_f32 v152, v64, v65
	v_cvt_pk_bf16_f32 v153, v66, v67
	v_cvt_pk_bf16_f32 v154, v68, v69
	v_cvt_pk_bf16_f32 v155, v70, v71
	s_nop 1
	global_store_dwordx4 v132, v[152:155], s[50:51]
	s_nop 1
	v_fmamk_f32 v131, v139, 0x3a000000, v130
	v_add_u32_e32 v132, 0x18c000, v129
	v_rsq_f32_e32 v131, v131
	s_nop 0
	v_mul_f32_e32 v72, v72, v131
	v_mul_f32_e32 v73, v73, v131
	v_mul_f32_e32 v74, v74, v131
	v_mul_f32_e32 v75, v75, v131
	v_mul_f32_e32 v76, v76, v131
	v_mul_f32_e32 v77, v77, v131
	v_mul_f32_e32 v78, v78, v131
	v_mul_f32_e32 v79, v79, v131
	v_mul_f32_e32 v104, v104, v131
	v_mul_f32_e32 v105, v105, v131
	v_mul_f32_e32 v106, v106, v131
	v_mul_f32_e32 v107, v107, v131
	v_mul_f32_e32 v108, v108, v131
	v_mul_f32_e32 v109, v109, v131
	v_mul_f32_e32 v110, v110, v131
	v_mul_f32_e32 v111, v111, v131
	v_mul_f32_e32 v144, 0xbfb8aa3b, v72
	v_mul_f32_e32 v145, 0xbfb8aa3b, v73
	v_mul_f32_e32 v146, 0xbfb8aa3b, v74
	v_mul_f32_e32 v147, 0xbfb8aa3b, v75
	v_mul_f32_e32 v148, 0xbfb8aa3b, v76
	v_mul_f32_e32 v149, 0xbfb8aa3b, v77
	v_mul_f32_e32 v150, 0xbfb8aa3b, v78
	v_mul_f32_e32 v151, 0xbfb8aa3b, v79
	v_exp_f32_e32 v144, v144
	v_exp_f32_e32 v145, v145
	v_exp_f32_e32 v146, v146
	v_exp_f32_e32 v147, v147
	v_exp_f32_e32 v148, v148
	v_exp_f32_e32 v149, v149
	v_exp_f32_e32 v150, v150
	v_exp_f32_e32 v151, v151
	v_add_f32_e32 v144, 1.0, v144
	v_add_f32_e32 v145, 1.0, v145
	v_add_f32_e32 v146, 1.0, v146
	v_add_f32_e32 v147, 1.0, v147
	v_add_f32_e32 v148, 1.0, v148
	v_add_f32_e32 v149, 1.0, v149
	v_add_f32_e32 v150, 1.0, v150
	v_add_f32_e32 v151, 1.0, v151
	v_rcp_f32_e32 v144, v144
	v_rcp_f32_e32 v145, v145
	v_rcp_f32_e32 v146, v146
	v_rcp_f32_e32 v147, v147
	v_rcp_f32_e32 v148, v148
	v_rcp_f32_e32 v149, v149
	v_rcp_f32_e32 v150, v150
	v_rcp_f32_e32 v151, v151
	v_mul_f32_e32 v72, v72, v144
	v_mul_f32_e32 v73, v73, v145
	v_mul_f32_e32 v74, v74, v146
	v_mul_f32_e32 v75, v75, v147
	v_mul_f32_e32 v76, v76, v148
	v_mul_f32_e32 v77, v77, v149
	v_mul_f32_e32 v78, v78, v150
	v_mul_f32_e32 v79, v79, v151
	v_mul_f32_e32 v72, v104, v72
	v_mul_f32_e32 v73, v105, v73
	v_mul_f32_e32 v74, v106, v74
	v_mul_f32_e32 v75, v107, v75
	v_mul_f32_e32 v76, v108, v76
	v_mul_f32_e32 v77, v109, v77
	v_mul_f32_e32 v78, v110, v78
	v_mul_f32_e32 v79, v111, v79
	v_cvt_pk_bf16_f32 v152, v72, v73
	v_cvt_pk_bf16_f32 v153, v74, v75
	v_cvt_pk_bf16_f32 v154, v76, v77
	v_cvt_pk_bf16_f32 v155, v78, v79
	s_nop 1
	global_store_dwordx4 v132, v[152:155], s[50:51]
	s_nop 1
	v_fmamk_f32 v131, v140, 0x3a000000, v130
	v_add_u32_e32 v132, 0x1b8000, v129
	v_rsq_f32_e32 v131, v131
	s_nop 0
	v_mul_f32_e32 v80, v80, v131
	v_mul_f32_e32 v81, v81, v131
	v_mul_f32_e32 v82, v82, v131
	v_mul_f32_e32 v83, v83, v131
	v_mul_f32_e32 v84, v84, v131
	v_mul_f32_e32 v85, v85, v131
	v_mul_f32_e32 v86, v86, v131
	v_mul_f32_e32 v87, v87, v131
	v_mul_f32_e32 v112, v112, v131
	v_mul_f32_e32 v113, v113, v131
	v_mul_f32_e32 v114, v114, v131
	v_mul_f32_e32 v115, v115, v131
	v_mul_f32_e32 v116, v116, v131
	v_mul_f32_e32 v117, v117, v131
	v_mul_f32_e32 v118, v118, v131
	v_mul_f32_e32 v119, v119, v131
	v_mul_f32_e32 v144, 0xbfb8aa3b, v80
	v_mul_f32_e32 v145, 0xbfb8aa3b, v81
	v_mul_f32_e32 v146, 0xbfb8aa3b, v82
	v_mul_f32_e32 v147, 0xbfb8aa3b, v83
	v_mul_f32_e32 v148, 0xbfb8aa3b, v84
	v_mul_f32_e32 v149, 0xbfb8aa3b, v85
; __device__ __forceinline__ unsigned cvt_pk_bf16(float lo, float hi) { unsigned r; asm volatile("v_cvt_pk_bf16_f32 %0, %1, %2" : "=v"(r) : "v"(lo), "v"(hi)); return r; }
;     __device__ __forceinline__ void operator()(const f32x4 (&acc)[2][2][4][2], const Unit& u, int wr, int wc, int fr, int fq) const {
;     ...
; #pragma unroll
;         for (int ai = 0; ai < 2; ++ai)
; #pragma unroll
;             for (int m = 0; m < 4; ++m) { const int row = row0 + ai * HALF + m * 16; const float rs = __builtin_amdgcn_rsqf(rsv[ai][m] * inv_n + eps);
;                 float a[8];
; #pragma unroll
;                 for (int n = 0; n < 2; ++n)
; #pragma unroll
;                     for (int i = 0; i < 4; ++i) { const float g = acc[ai][0][m][n][i] * rs, up = acc[ai][1][m][n][i] * rs;
;                         a[n * 4 + i] = g * __builtin_amdgcn_rcpf(1.0f + __builtin_amdgcn_exp2f(-1.4426950408889634f * g)) * up; }
;                 u32x4 w; w.x = cvt_pk_bf16(a[0], a[1]); w.y = cvt_pk_bf16(a[2], a[3]); w.z = cvt_pk_bf16(a[4], a[5]); w.w = cvt_pk_bf16(a[6], a[7]);
;                 *(u32x4*)(O + (size_t)row * ldc + col0) = w; }
;     }
; template <class Epi, class Sched, bool ALIGN_EPI = false, bool SP2 = false>
; __device__ __forceinline__ void gemm_phase(PG8_LAS unsigned char* lds, const Gemm g, const Sched& S, const Epi& E) {
;     ...
;         if constexpr (!Epi::AFTER_DRAIN) { E(acc, cur, wr, wc, fr, fq); S.done(cur); }
;         if (!has_next) break;
; #pragma unroll
;         for (int a = 0; a < 2; ++a)
; #pragma unroll
;             for (int b = 0; b < 2; ++b)
; #pragma unroll
;                 for (int m = 0; m < 4; ++m)
; #pragma unroll
;                     for (int n = 0; n < 2; ++n) acc[a][b][m][n] = (f32x4){0.f, 0.f, 0.f, 0.f};
;         cur = nxt; cA = nA; cB = nB; ++ui;
	v_mul_f32_e32 v150, 0xbfb8aa3b, v86
	v_mul_f32_e32 v151, 0xbfb8aa3b, v87
	v_exp_f32_e32 v144, v144
	v_exp_f32_e32 v145, v145
	v_exp_f32_e32 v146, v146
	v_exp_f32_e32 v147, v147
	v_exp_f32_e32 v148, v148
	v_exp_f32_e32 v149, v149
	v_exp_f32_e32 v150, v150
	v_exp_f32_e32 v151, v151
	v_add_f32_e32 v144, 1.0, v144
	v_add_f32_e32 v145, 1.0, v145
	v_add_f32_e32 v146, 1.0, v146
	v_add_f32_e32 v147, 1.0, v147
	v_add_f32_e32 v148, 1.0, v148
	v_add_f32_e32 v149, 1.0, v149
	v_add_f32_e32 v150, 1.0, v150
	v_add_f32_e32 v151, 1.0, v151
	v_rcp_f32_e32 v144, v144
	v_rcp_f32_e32 v145, v145
	v_rcp_f32_e32 v146, v146
	v_rcp_f32_e32 v147, v147
	v_rcp_f32_e32 v148, v148
	v_rcp_f32_e32 v149, v149
	v_rcp_f32_e32 v150, v150
	v_rcp_f32_e32 v151, v151
	v_mul_f32_e32 v80, v80, v144
	v_mul_f32_e32 v81, v81, v145
	v_mul_f32_e32 v82, v82, v146
	v_mul_f32_e32 v83, v83, v147
	v_mul_f32_e32 v84, v84, v148
	v_mul_f32_e32 v85, v85, v149
	v_mul_f32_e32 v86, v86, v150
	v_mul_f32_e32 v87, v87, v151
	v_mul_f32_e32 v80, v112, v80
	v_mul_f32_e32 v81, v113, v81
	v_mul_f32_e32 v82, v114, v82
	v_mul_f32_e32 v83, v115, v83
	v_mul_f32_e32 v84, v116, v84
	v_mul_f32_e32 v85, v117, v85
	v_mul_f32_e32 v86, v118, v86
	v_mul_f32_e32 v87, v119, v87
	v_cvt_pk_bf16_f32 v152, v80, v81
	v_cvt_pk_bf16_f32 v153, v82, v83
	v_cvt_pk_bf16_f32 v154, v84, v85
	v_cvt_pk_bf16_f32 v155, v86, v87
	s_nop 1
	global_store_dwordx4 v132, v[152:155], s[50:51]
	s_nop 1
	v_fmamk_f32 v131, v141, 0x3a000000, v130
	v_add_u32_e32 v132, 0x1e4000, v129
	v_rsq_f32_e32 v131, v131
	s_nop 0
	v_mul_f32_e32 v88, v88, v131
	v_mul_f32_e32 v89, v89, v131
	v_mul_f32_e32 v90, v90, v131
	v_mul_f32_e32 v91, v91, v131
	v_mul_f32_e32 v92, v92, v131
	v_mul_f32_e32 v93, v93, v131
	v_mul_f32_e32 v94, v94, v131
	v_mul_f32_e32 v95, v95, v131
	v_mul_f32_e32 v120, v120, v131
	v_mul_f32_e32 v121, v121, v131
	v_mul_f32_e32 v122, v122, v131
	v_mul_f32_e32 v123, v123, v131
	v_mul_f32_e32 v124, v124, v131
	v_mul_f32_e32 v125, v125, v131
	v_mul_f32_e32 v126, v126, v131
	v_mul_f32_e32 v127, v127, v131
	v_mul_f32_e32 v144, 0xbfb8aa3b, v88
	v_mul_f32_e32 v145, 0xbfb8aa3b, v89
	v_mul_f32_e32 v146, 0xbfb8aa3b, v90
	v_mul_f32_e32 v147, 0xbfb8aa3b, v91
	v_mul_f32_e32 v148, 0xbfb8aa3b, v92
	v_mul_f32_e32 v149, 0xbfb8aa3b, v93
	v_mul_f32_e32 v150, 0xbfb8aa3b, v94
	v_mul_f32_e32 v151, 0xbfb8aa3b, v95
	v_exp_f32_e32 v144, v144
	v_exp_f32_e32 v145, v145
	v_exp_f32_e32 v146, v146
	v_exp_f32_e32 v147, v147
	v_exp_f32_e32 v148, v148
	v_exp_f32_e32 v149, v149
	v_exp_f32_e32 v150, v150
	v_exp_f32_e32 v151, v151
	v_add_f32_e32 v144, 1.0, v144
	v_add_f32_e32 v145, 1.0, v145
	v_add_f32_e32 v146, 1.0, v146
	v_add_f32_e32 v147, 1.0, v147
	v_add_f32_e32 v148, 1.0, v148
	v_add_f32_e32 v149, 1.0, v149
	v_add_f32_e32 v150, 1.0, v150
	v_add_f32_e32 v151, 1.0, v151
	v_rcp_f32_e32 v144, v144
	v_rcp_f32_e32 v145, v145
	v_rcp_f32_e32 v146, v146
	v_rcp_f32_e32 v147, v147
	v_rcp_f32_e32 v148, v148
	v_rcp_f32_e32 v149, v149
	v_rcp_f32_e32 v150, v150
	v_rcp_f32_e32 v151, v151
	v_mul_f32_e32 v88, v88, v144
	v_mul_f32_e32 v89, v89, v145
	v_mul_f32_e32 v90, v90, v146
	v_mul_f32_e32 v91, v91, v147
	v_mul_f32_e32 v92, v92, v148
	v_mul_f32_e32 v93, v93, v149
	v_mul_f32_e32 v94, v94, v150
	v_mul_f32_e32 v95, v95, v151
	v_mul_f32_e32 v88, v120, v88
	v_mul_f32_e32 v89, v121, v89
	v_mul_f32_e32 v90, v122, v90
	v_mul_f32_e32 v91, v123, v91
	v_mul_f32_e32 v92, v124, v92
	v_mul_f32_e32 v93, v125, v93
	v_mul_f32_e32 v94, v126, v94
	v_mul_f32_e32 v95, v127, v95
	v_cvt_pk_bf16_f32 v152, v88, v89
	v_cvt_pk_bf16_f32 v153, v90, v91
	v_cvt_pk_bf16_f32 v154, v92, v93
	v_cvt_pk_bf16_f32 v155, v94, v95
	s_nop 1
	global_store_dwordx4 v132, v[152:155], s[50:51]
	s_nop 1
	s_cmp_eq_u32 s19, 0
	s_cbranch_scc1 .Lp5_done
	s_mov_b32 s17, s20
	s_mov_b32 s18, s21
	s_mov_b64 s[22:23], s[26:27]
	s_mov_b64 s[24:25], s[28:29]
	s_add_u32 s16, s16, 1
	s_branch .Lp5_unit
